# 7.11 complete form for the NA tile loop too: next tile's loads in front of the per-tile barrier and fall-through from the barrier into the tile body (entry head relocated behind the item prologue)
# speedup vs baseline: 1.0054x; 1.0006x over previous
.LBB0_333:
	v_lshl_add_u32 v0, s34, 9, v115
	s_waitcnt lgkmcnt(0)
	v_mov_b32_e32 v12, v163
	v_ashrrev_i32_e32 v0, 9, v0
	v_bfe_u32 v5, v12, 7, 1
	s_movk_i32 s2, 0x1100
	v_or_b32_e32 v8, v5, v127
	v_mad_i32_i24 v139, v0, s2, v188
	v_lshrrev_b32_e32 v2, 1, v12
	v_and_b32_e32 v138, 15, v12
	v_bfe_u32 v7, v12, 4, 2
	v_mul_i32_i24_e32 v4, 0x1100, v0
	v_lshl_add_u32 v0, v8, 6, v139
	v_and_b32_e32 v6, 32, v2
	v_or3_b32 v122, v0, v6, v138
	v_lshlrev_b32_e32 v0, 4, v7
	v_lshl_add_u64 v[2:3], v[116:117], 0, v[0:1]
	s_movk_i32 s4, 0x1800
	v_or_b32_e32 v120, 16, v122
	v_bfe_u32 v141, v12, 3, 5
	v_mad_i64_i32 v[10:11], s[2:3], v122, s4, v[2:3]
	v_mad_i64_i32 v[2:3], s[2:3], v120, s4, v[2:3]
	v_add_u32_e32 v18, v139, v129
	v_or_b32_e32 v143, 32, v141
	v_and_b32_e32 v28, 0xff, v12
	global_load_dwordx4 v[38:41], v[10:11], off
	global_load_dwordx4 v[34:37], v[10:11], off offset:64
	global_load_dwordx4 v[46:49], v[2:3], off
	global_load_dwordx4 v[42:45], v[2:3], off offset:64
	v_readlane_b32 s6, v252, 60
	v_readlane_b32 s7, v252, 61
	v_add_lshl_u32 v50, v130, v28, 2
	v_mov_b32_e32 v51, 0
	v_cmp_ge_u32_e32 vcc, s12, v28
	v_lshl_add_u64 v[50:51], s[6:7], 0, v[50:51]
	global_load_dword v52, v[50:51], off
	s_and_saveexec_b64 s[6:7], vcc
	global_load_dword v53, v[50:51], off offset:1024
	s_mov_b64 exec, s[6:7]
	v_or_b32_e32 v0, v141, v18
	v_mov_b64_e32 v[2:3], s[26:27]
	v_lshlrev_b32_e32 v12, 3, v12
	v_or_b32_e32 v18, v143, v18
	v_mad_i64_i32 v[10:11], s[2:3], v0, s4, v[2:3]
	v_lshlrev_b32_e32 v0, 1, v114
	v_and_b32_e32 v124, 56, v12
	v_mad_i64_i32 v[2:3], s[2:3], v18, s4, v[2:3]
	v_lshl_add_u64 v[10:11], v[10:11], 0, v[0:1]
	v_lshlrev_b32_e32 v26, 1, v124
	v_mov_b32_e32 v27, v1
	v_lshl_add_u64 v[2:3], v[2:3], 0, v[0:1]
	v_lshl_add_u64 v[14:15], v[10:11], 0, v[26:27]
	s_movk_i32 s5, 0x1000
	v_lshl_add_u64 v[2:3], v[2:3], 0, v[26:27]
	global_load_dwordx4 v[10:13], v[14:15], off offset:2048
	global_load_dwordx4 v[18:21], v[2:3], off offset:2048
	v_add_co_u32_e32 v14, vcc, s5, v14
	v_readlane_b32 s2, v252, 60
	s_nop 0
	v_addc_co_u32_e32 v15, vcc, 0, v15, vcc
	global_load_dwordx4 v[14:17], v[14:15], off
	v_add_co_u32_e32 v2, vcc, s5, v2
	v_readlane_b32 s3, v252, 61
	s_nop 0
	v_addc_co_u32_e32 v3, vcc, 0, v3, vcc
	global_load_dwordx4 v[22:25], v[2:3], off
	v_mul_u32_u24_e32 v2, 0x48, v141
	v_lshlrev_b32_e32 v2, 1, v2
	v_add3_u32 v2, v222, v2, v26
	v_mov_b32_e32 v3, v1
	v_lshlrev_b32_e32 v9, 3, v7
	v_ashrrev_i32_e32 v123, 31, v122
	v_ashrrev_i32_e32 v121, 31, v120
	s_mov_b64 s[4:5], 0
	s_waitcnt vmcnt(3)
	ds_write_b128 v2, v[10:13]
	s_waitcnt vmcnt(1)
	ds_write_b128 v2, v[14:17] offset:18432
	ds_write_b128 v2, v[18:21] offset:4608
	s_waitcnt vmcnt(0)
	ds_write_b128 v2, v[22:25] offset:23040
	v_lshlrev_b32_e32 v10, 2, v28
	v_add_u32_e32 v11, v131, v10
	v_mul_f32_e32 v52, 0x3fb8aa3b, v52
	v_cmp_ge_u32_e32 vcc, s12, v28
	ds_write_b32 v11, v52
	s_and_saveexec_b64 s[4:5], vcc
	v_mul_f32_e32 v53, 0x3fb8aa3b, v53
	ds_write_b32 v11, v53 offset:1024
	s_or_b64 exec, exec, s[4:5]
	v_lshlrev_b32_e32 v134, 2, v7
	v_lshrrev_b32_e32 v7, 2, v138
	v_or_b32_e32 v3, v6, v138
	v_or_b32_e32 v135, v134, v7
	v_and_b32_e32 v7, 12, v10
	v_lshl_add_u32 v136, v7, 1, v222
	v_sub_u32_e64 v7, v3, 8 clamp
	v_sub_u32_e32 v7, v134, v7
	v_sub_u32_e64 v2, v8, 4 clamp
	v_add_u32_e32 v8, 1, v7
	v_cmp_gt_u32_e64 s[42:43], 16, v8
	v_add_u32_e32 v8, 2, v7
	v_cmp_gt_u32_e64 s[44:45], 16, v8
	v_add_u32_e32 v8, 3, v7
	v_cmp_gt_u32_e64 s[46:47], 16, v8
	v_add_u32_e32 v8, 17, v7
	v_cmp_gt_u32_e64 s[50:51], 16, v8
	v_add_u32_e32 v8, 18, v7
	v_cmp_gt_u32_e64 s[52:53], 16, v8
	v_add_u32_e32 v8, 19, v7
	v_cmp_gt_u32_e64 s[54:55], 16, v8
	v_and_b32_e32 v8, -16, v7
	s_movk_i32 s3, 0xffe0
	s_movk_i32 s6, 0xffd0
	v_cmp_eq_u32_e64 s[56:57], s3, v8
	v_cmp_eq_u32_e64 s[64:65], s6, v8
	v_add_u32_e32 v8, 49, v7
	v_min_u32_e32 v3, 40, v3
	v_cmp_gt_u32_e64 s[66:67], 16, v8
	v_add_u32_e32 v8, 50, v7
	v_sub_u32_e32 v3, v134, v3
	v_cmp_gt_u32_e64 s[68:69], 16, v8
	v_add_u32_e32 v8, -7, v3
	v_cmp_gt_u32_e64 s[74:75], 16, v8
	v_add_u32_e32 v8, -6, v3
	v_lshl_add_u32 v145, v9, 1, v222
	v_add_u32_e32 v9, 33, v7
	v_cmp_gt_u32_e64 s[76:77], 16, v8
	v_add_u32_e32 v8, -5, v3
	s_movk_i32 s2, 0xffef
	v_cmp_gt_u32_e64 s[58:59], 16, v9
	v_add_u32_e32 v9, 34, v7
	v_cmp_gt_u32_e64 s[78:79], 16, v8
	v_add_u32_e32 v8, 9, v3
	v_cmp_gt_u32_e64 s[40:41], 16, v7
	v_cmp_lt_u32_e64 s[48:49], s2, v7
	v_cmp_gt_u32_e64 s[60:61], 16, v9
	v_add_u32_e32 v9, 35, v7
	v_add_u32_e32 v7, 51, v7
	v_cmp_gt_u32_e64 s[82:83], 16, v8
	v_add_u32_e32 v8, 10, v3
	v_cmp_gt_u32_e64 s[70:71], 16, v7
	v_add_u32_e32 v7, -8, v3
	v_cmp_gt_u32_e64 s[84:85], 16, v8
	v_add_u32_e32 v8, 11, v3
	v_cmp_gt_u32_e64 s[72:73], 16, v7
	v_cmp_lt_u32_e64 s[80:81], s2, v7
	v_cmp_gt_u32_e64 s[86:87], 16, v8
	v_and_b32_e32 v7, -16, v7
	v_add_u32_e32 v8, 25, v3
	v_cmp_eq_u32_e64 s[88:89], s3, v7
	v_cmp_gt_u32_e64 s[90:91], 16, v8
	v_add_u32_e32 v8, 26, v3
	v_cmp_eq_u32_e64 s[94:95], s6, v7
	v_add_u32_e32 v7, 41, v3
	v_cmp_gt_u32_e64 s[92:93], 16, v8
	v_add_u32_e32 v8, 27, v3
	v_cmp_gt_u32_e64 s[6:7], 16, v7
	v_add_u32_e32 v7, 42, v3
	v_add_u32_e32 v3, 43, v3
	v_cmp_gt_u32_e64 s[96:97], 16, v3
	v_sub_u32_e32 v3, v132, v5
	v_sub_u32_e32 v5, v134, v138
	v_sub_u32_e32 v5, v5, v6
	v_min_u32_e32 v2, 56, v2
	v_mul_i32_i24_e32 v3, 0x7c, v3
	v_lshlrev_b32_e32 v5, 2, v5
	v_mov_b32_e32 v18, v1
	v_mov_b32_e32 v19, v1
	v_mov_b32_e32 v20, v1
	v_mov_b32_e32 v21, v1
	v_cmp_gt_u32_e64 s[62:63], 16, v9
	v_cmp_gt_u32_e64 s[4:5], 16, v8
	v_cmp_gt_u32_e64 s[8:9], 16, v7
	v_add3_u32 v147, v3, v5, v126
	v_sub_u32_e32 v148, v128, v2
	v_add_u32_e32 v149, 0xfffffe00, v4
	v_mov_b64_e32 v[32:33], v[20:21]
	v_mov_b64_e32 v[24:25], v[20:21]
	v_mov_b64_e32 v[28:29], v[20:21]
	v_mov_b64_e32 v[10:11], v[18:19]
	v_mov_b64_e32 v[14:15], v[18:19]
	v_mov_b64_e32 v[2:3], v[18:19]
	v_mov_b64_e32 v[6:7], v[18:19]
	v_lshl_add_u32 v146, v124, 1, v222
	s_mov_b32 s14, 0
	v_mov_b32_e32 v144, 0xf149f2ca
	v_mov_b32_e32 v140, 0
	v_mov_b64_e32 v[30:31], v[18:19]
	v_mov_b64_e32 v[22:23], v[18:19]
	v_mov_b64_e32 v[26:27], v[18:19]
	v_mov_b64_e32 v[12:13], v[20:21]
	v_mov_b64_e32 v[16:17], v[20:21]
	v_mov_b64_e32 v[4:5], v[20:21]
	v_mov_b64_e32 v[8:9], v[20:21]
	v_mov_b32_e32 v137, 0
	v_mov_b32_e32 v142, 0xf149f2ca
	s_mov_b32 s24, 0
	s_waitcnt lgkmcnt(0)
	s_barrier
.LBB0_338:
	s_cmp_gt_u32 s24, 7
	s_mov_b64 s[2:3], -1
	s_cbranch_scc0 .LBB0_340
	v_add_u32_e32 v58, s14, v149
	s_mov_b64 s[2:3], 0

.LBB0_342:
	v_add_u32_e32 v50, v58, v141
	v_mov_b64_e32 v[60:61], s[26:27]
	s_movk_i32 s10, 0x1800
	v_mad_i64_i32 v[50:51], s[2:3], v50, s10, v[60:61]
	v_lshl_add_u64 v[50:51], v[50:51], 0, v[0:1]
	v_lshlrev_b32_e32 v62, 1, v124
	v_mov_b32_e32 v63, v1
	v_add_u32_e32 v58, v58, v143
	v_lshl_add_u64 v[50:51], v[50:51], 0, v[62:63]
	v_mad_i64_i32 v[58:59], s[2:3], v58, s10, v[60:61]
	v_add_co_u32_e32 v54, vcc, 0x1000, v50
	v_lshl_add_u64 v[58:59], v[58:59], 0, v[0:1]
	s_nop 0
	v_addc_co_u32_e32 v55, vcc, 0, v51, vcc
	v_lshl_add_u64 v[58:59], v[58:59], 0, v[62:63]
	v_add_co_u32_e32 v62, vcc, 0x1000, v58
	global_load_dwordx4 v[50:53], v[50:51], off offset:2048
	s_nop 0
	global_load_dwordx4 v[54:57], v[54:55], off
	v_addc_co_u32_e32 v63, vcc, 0, v59, vcc
	global_load_dwordx4 v[58:61], v[58:59], off offset:2048
	s_nop 0
	global_load_dwordx4 v[62:65], v[62:63], off
	s_branch .Lna_rot_body

.Lna_rot_skip:
	s_cmp_lg_u32 s24, 12
	s_barrier
	s_cbranch_scc0 .LBB0_419
